# non-temporal loads for the read-once streams of the S5 combine phase and for the gate slice read by the retention combine phase
# speedup vs baseline: 1.0080x; 1.0060x over previous
; DI void unpack8(u32x4 v, float* f) { f[0] = bflo(v.x); f[1] = bfhi(v.x); f[2] = bflo(v.y); f[3] = bfhi(v.y); f[4] = bflo(v.z); f[5] = bfhi(v.z); f[6] = bflo(v.w); f[7] = bfhi(v.w); }
; DI u32x4 pack8(const float* f) { u32x4 o; o.x = pk2(f[0], f[1]); o.y = pk2(f[2], f[3]); o.z = pk2(f[4], f[5]); o.w = pk2(f[6], f[7]); return o; }
; DI float gelu_tanh(float x) { const float z = 0.7978845608028654f * (x + 0.044715f * x * x * x); const float e = __expf(2.f * z); const float th = 1.f - 2.f / (e + 1.f); return 0.5f * x * (1.f + th); }
; DI void s5comb_phase(const bf16_t* H, const bf16_t* YF, const bf16_t* YB, const float* dsk, bf16_t* Gb, int nrows, int gt, int GT) {
;     const size_t n8 = (size_t)nrows * (D / 8);
;     for (size_t i = gt; i < n8; i += GT) {
;         const int c = (int)(i & 127) * 8;
;         float u[8], f1[8], f2[8], o[8];
;         unpack8(*(const u32x4*)(H + i * 8), u); unpack8(*(const u32x4*)(YF + i * 8), f1); unpack8(*(const u32x4*)(YB + i * 8), f2);
;         const f32x4 d0 = *(const f32x4*)(dsk + c), d1 = *(const f32x4*)(dsk + c + 4);
; #pragma unroll
;         for (int q = 0; q < 8; ++q) { const float dd = q < 4 ? d0[q] : d1[q - 4]; o[q] = gelu_tanh(f1[q] + f2[q] + dd * u[q]); }
;         *(u32x4*)(Gb + i * 8) = pack8(o);
;     }
; }
.LBB0_389:
	v_add_co_u32_e32 v6, vcc, 0xef000000, v0
	v_and_b32_e32 v18, 0x3f8, v2
	s_nop 0
	v_addc_co_u32_e32 v7, vcc, -1, v1, vcc
	v_add_co_u32_e32 v10, vcc, 0xf7800000, v0
	global_load_dwordx4 v[6:9], v[6:7], off nt
	s_nop 0
	v_addc_co_u32_e32 v11, vcc, -1, v1, vcc
	global_load_dwordx4 v[10:13], v[10:11], off nt
	s_nop 0
	global_load_dwordx4 v[14:17], v[0:1], off nt
	v_lshlrev_b32_e32 v22, 2, v18
	global_load_dwordx4 v[18:21], v22, s[4:5] offset:16
	s_nop 0
	global_load_dwordx4 v[22:25], v22, s[4:5]
	v_lshl_add_u64 v[4:5], v[4:5], 0, s[86:87]
	v_lshl_add_u64 v[2:3], v[2:3], 0, s[8:9]
	s_waitcnt vmcnt(4)
	v_lshlrev_b32_e32 v26, 16, v6
	v_and_b32_e32 v27, 0xffff0000, v6
	s_waitcnt vmcnt(3)
	v_lshlrev_b32_e32 v28, 16, v10
	v_and_b32_e32 v29, 0xffff0000, v10
	s_waitcnt vmcnt(2)
	v_lshlrev_b32_e32 v30, 16, v14
	v_and_b32_e32 v31, 0xffff0000, v14
	v_pk_add_f32 v[28:29], v[28:29], v[30:31]
	s_waitcnt vmcnt(0)
	v_pk_fma_f32 v[22:23], v[22:23], v[26:27], v[28:29]
	s_nop 0
	v_mul_f32_e32 v6, 0x3d372713, v22
	v_mul_f32_e32 v6, v22, v6
	v_fma_f32 v6, v22, v6, v22
	v_mul_f32_e32 v6, 0x3f4c422a, v6
	v_add_f32_e32 v6, v6, v6
	v_mul_f32_e32 v6, 0x3fb8aa3b, v6
	v_exp_f32_e32 v26, v6
	v_mul_f32_e32 v6, 0x3d372713, v23
	v_mul_f32_e32 v6, v23, v6
	v_fma_f32 v6, v23, v6, v23
	v_mul_f32_e32 v6, 0x3f4c422a, v6
	v_add_f32_e32 v6, v6, v6
	v_mul_f32_e32 v6, 0x3fb8aa3b, v6
	v_exp_f32_e32 v27, v6
	v_pk_mul_f32 v[22:23], v[22:23], 0.5 op_sel_hi:[1,0]
	v_pk_add_f32 v[26:27], v[26:27], 1.0 op_sel_hi:[1,0]
	s_nop 0
	v_div_scale_f32 v6, s[24:25], v27, v27, 2.0
	v_rcp_f32_e32 v10, v6
	s_nop 0
	v_fma_f32 v14, -v6, v10, 1.0
	v_fmac_f32_e32 v10, v14, v10
	v_div_scale_f32 v14, vcc, 2.0, v27, 2.0
	v_mul_f32_e32 v28, v14, v10
	v_fma_f32 v29, -v6, v28, v14
	v_fmac_f32_e32 v28, v29, v10
	v_fma_f32 v6, -v6, v28, v14
	v_div_fmas_f32 v6, v6, v10, v28
	v_div_fixup_f32 v27, v6, v27, 2.0
	v_div_scale_f32 v6, s[24:25], v26, v26, 2.0
	v_rcp_f32_e32 v10, v6
	s_nop 0
	v_fma_f32 v14, -v6, v10, 1.0
	v_fmac_f32_e32 v10, v14, v10
	v_div_scale_f32 v14, vcc, 2.0, v26, 2.0
	v_mul_f32_e32 v28, v14, v10
	v_fma_f32 v29, -v6, v28, v14
	v_fmac_f32_e32 v28, v29, v10
	v_fma_f32 v6, -v6, v28, v14
	v_div_fmas_f32 v6, v6, v10, v28
	v_lshlrev_b32_e32 v10, 16, v11
	v_and_b32_e32 v11, 0xffff0000, v11
	v_lshlrev_b32_e32 v14, 16, v15
	v_and_b32_e32 v15, 0xffff0000, v15
	v_div_fixup_f32 v26, v6, v26, 2.0
	v_lshlrev_b32_e32 v6, 16, v7
	v_and_b32_e32 v7, 0xffff0000, v7
	v_pk_add_f32 v[10:11], v[10:11], v[14:15]
	v_pk_add_f32 v[26:27], v[26:27], 1.0 op_sel_hi:[1,0] neg_lo:[1,0] neg_hi:[1,0]
	v_pk_fma_f32 v[6:7], v[24:25], v[6:7], v[10:11]
	v_pk_add_f32 v[26:27], v[26:27], 1.0 op_sel_hi:[1,0]
	v_mul_f32_e32 v10, 0x3d372713, v6
	v_mul_f32_e32 v11, 0x3d372713, v7
	v_mul_f32_e32 v10, v6, v10
	v_mul_f32_e32 v11, v7, v11
	v_fma_f32 v10, v6, v10, v6
	v_fma_f32 v11, v7, v11, v7
	v_mul_f32_e32 v10, 0x3f4c422a, v10
	v_mul_f32_e32 v11, 0x3f4c422a, v11
	v_add_f32_e32 v10, v10, v10
	v_add_f32_e32 v11, v11, v11
	v_mul_f32_e32 v10, 0x3fb8aa3b, v10
	v_mul_f32_e32 v11, 0x3fb8aa3b, v11
	v_exp_f32_e32 v10, v10
	v_exp_f32_e32 v11, v11
	v_pk_mul_f32 v[22:23], v[22:23], v[26:27]
	v_pk_mul_f32 v[6:7], v[6:7], 0.5 op_sel_hi:[1,0]
	v_pk_add_f32 v[10:11], v[10:11], 1.0 op_sel_hi:[1,0]
	s_nop 0
	v_div_scale_f32 v14, s[24:25], v11, v11, 2.0
	v_rcp_f32_e32 v15, v14
	s_nop 0
	v_fma_f32 v24, -v14, v15, 1.0
	v_fmac_f32_e32 v15, v24, v15
	v_div_scale_f32 v24, vcc, 2.0, v11, 2.0
	v_mul_f32_e32 v25, v24, v15
	v_fma_f32 v26, -v14, v25, v24
	v_fmac_f32_e32 v25, v26, v15
	v_fma_f32 v14, -v14, v25, v24
	v_div_fmas_f32 v14, v14, v15, v25
	v_div_fixup_f32 v11, v14, v11, 2.0
	v_div_scale_f32 v14, s[24:25], v10, v10, 2.0
	v_rcp_f32_e32 v15, v14
	s_nop 0
	v_fma_f32 v24, -v14, v15, 1.0
	v_fmac_f32_e32 v15, v24, v15
	v_div_scale_f32 v24, vcc, 2.0, v10, 2.0
	v_mul_f32_e32 v25, v24, v15
	v_fma_f32 v26, -v14, v25, v24
	v_fmac_f32_e32 v25, v26, v15
	v_fma_f32 v14, -v14, v25, v24
	v_div_fmas_f32 v14, v14, v15, v25
	v_div_fixup_f32 v10, v14, v10, 2.0
	v_pk_add_f32 v[10:11], v[10:11], 1.0 op_sel_hi:[1,0] neg_lo:[1,0] neg_hi:[1,0]
; DI void unpack8(u32x4 v, float* f) { f[0] = bflo(v.x); f[1] = bfhi(v.x); f[2] = bflo(v.y); f[3] = bfhi(v.y); f[4] = bflo(v.z); f[5] = bfhi(v.z); f[6] = bflo(v.w); f[7] = bfhi(v.w); }
; DI u32x4 pack8(const float* f) { u32x4 o; o.x = pk2(f[0], f[1]); o.y = pk2(f[2], f[3]); o.z = pk2(f[4], f[5]); o.w = pk2(f[6], f[7]); return o; }
; DI float gelu_tanh(float x) { const float z = 0.7978845608028654f * (x + 0.044715f * x * x * x); const float e = __expf(2.f * z); const float th = 1.f - 2.f / (e + 1.f); return 0.5f * x * (1.f + th); }
; DI void s5comb_phase(const bf16_t* H, const bf16_t* YF, const bf16_t* YB, const float* dsk, bf16_t* Gb, int nrows, int gt, int GT) {
;     const size_t n8 = (size_t)nrows * (D / 8);
;     for (size_t i = gt; i < n8; i += GT) {
;         const int c = (int)(i & 127) * 8;
;         float u[8], f1[8], f2[8], o[8];
;         unpack8(*(const u32x4*)(H + i * 8), u); unpack8(*(const u32x4*)(YF + i * 8), f1); unpack8(*(const u32x4*)(YB + i * 8), f2);
;         const f32x4 d0 = *(const f32x4*)(dsk + c), d1 = *(const f32x4*)(dsk + c + 4);
; #pragma unroll
;         for (int q = 0; q < 8; ++q) { const float dd = q < 4 ? d0[q] : d1[q - 4]; o[q] = gelu_tanh(f1[q] + f2[q] + dd * u[q]); }
;         *(u32x4*)(Gb + i * 8) = pack8(o);
;     }
	v_lshlrev_b32_e32 v14, 16, v12
	v_pk_add_f32 v[10:11], v[10:11], 1.0 op_sel_hi:[1,0]
	v_and_b32_e32 v15, 0xffff0000, v12
	v_lshlrev_b32_e32 v24, 16, v16
	v_and_b32_e32 v25, 0xffff0000, v16
	v_pk_mul_f32 v[10:11], v[6:7], v[10:11]
	v_lshlrev_b32_e32 v6, 16, v8
	v_and_b32_e32 v7, 0xffff0000, v8
	v_pk_add_f32 v[14:15], v[14:15], v[24:25]
	s_nop 0
	v_pk_fma_f32 v[6:7], v[18:19], v[6:7], v[14:15]
	s_nop 0
	v_mul_f32_e32 v8, 0x3d372713, v6
	v_mul_f32_e32 v8, v6, v8
	v_fma_f32 v8, v6, v8, v6
	v_mul_f32_e32 v8, 0x3f4c422a, v8
	v_add_f32_e32 v8, v8, v8
	v_mul_f32_e32 v8, 0x3fb8aa3b, v8
	v_exp_f32_e32 v14, v8
	v_mul_f32_e32 v8, 0x3d372713, v7
	v_mul_f32_e32 v8, v7, v8
	v_fma_f32 v8, v7, v8, v7
	v_mul_f32_e32 v8, 0x3f4c422a, v8
	v_add_f32_e32 v8, v8, v8
	v_mul_f32_e32 v8, 0x3fb8aa3b, v8
	v_exp_f32_e32 v15, v8
	v_pk_mul_f32 v[6:7], v[6:7], 0.5 op_sel_hi:[1,0]
	v_pk_add_f32 v[14:15], v[14:15], 1.0 op_sel_hi:[1,0]
	s_nop 0
	v_div_scale_f32 v8, s[24:25], v15, v15, 2.0
	v_rcp_f32_e32 v12, v8
	s_nop 0
	v_fma_f32 v16, -v8, v12, 1.0
	v_fmac_f32_e32 v12, v16, v12
	v_div_scale_f32 v16, vcc, 2.0, v15, 2.0
	v_mul_f32_e32 v18, v16, v12
	v_fma_f32 v19, -v8, v18, v16
	v_fmac_f32_e32 v18, v19, v12
	v_fma_f32 v8, -v8, v18, v16
	v_div_fmas_f32 v8, v8, v12, v18
	v_div_fixup_f32 v15, v8, v15, 2.0
	v_div_scale_f32 v8, s[24:25], v14, v14, 2.0
	v_rcp_f32_e32 v12, v8
	s_nop 0
	v_fma_f32 v16, -v8, v12, 1.0
	v_fmac_f32_e32 v12, v16, v12
	v_div_scale_f32 v16, vcc, 2.0, v14, 2.0
	v_mul_f32_e32 v18, v16, v12
	v_fma_f32 v19, -v8, v18, v16
	v_fmac_f32_e32 v18, v19, v12
	v_fma_f32 v8, -v8, v18, v16
	v_div_fmas_f32 v8, v8, v12, v18
	v_div_fixup_f32 v14, v8, v14, 2.0
	v_pk_add_f32 v[14:15], v[14:15], 1.0 op_sel_hi:[1,0] neg_lo:[1,0] neg_hi:[1,0]
	v_lshlrev_b32_e32 v8, 16, v13
	v_pk_add_f32 v[14:15], v[14:15], 1.0 op_sel_hi:[1,0]
	v_lshlrev_b32_e32 v12, 16, v17
	v_pk_mul_f32 v[14:15], v[6:7], v[14:15]
	v_lshlrev_b32_e32 v6, 16, v9
	v_and_b32_e32 v7, 0xffff0000, v9
	v_and_b32_e32 v9, 0xffff0000, v13
	v_and_b32_e32 v13, 0xffff0000, v17
	v_pk_add_f32 v[8:9], v[8:9], v[12:13]
	s_nop 0
	v_pk_fma_f32 v[6:7], v[20:21], v[6:7], v[8:9]
	s_nop 0
	v_mul_f32_e32 v8, 0x3d372713, v6
	v_mul_f32_e32 v9, 0x3d372713, v7
	v_mul_f32_e32 v8, v6, v8
	v_mul_f32_e32 v9, v7, v9
	v_fma_f32 v8, v6, v8, v6
	v_fma_f32 v9, v7, v9, v7
	v_mul_f32_e32 v8, 0x3f4c422a, v8
	v_mul_f32_e32 v9, 0x3f4c422a, v9
	v_add_f32_e32 v8, v8, v8
	v_add_f32_e32 v9, v9, v9
	v_mul_f32_e32 v8, 0x3fb8aa3b, v8
	v_mul_f32_e32 v9, 0x3fb8aa3b, v9
	v_exp_f32_e32 v8, v8
	v_exp_f32_e32 v9, v9
	v_pk_mul_f32 v[6:7], v[6:7], 0.5 op_sel_hi:[1,0]
	v_pk_add_f32 v[8:9], v[8:9], 1.0 op_sel_hi:[1,0]
	s_nop 0
	v_div_scale_f32 v12, s[24:25], v9, v9, 2.0
	v_rcp_f32_e32 v13, v12
	s_nop 0
	v_fma_f32 v16, -v12, v13, 1.0
	v_fmac_f32_e32 v13, v16, v13
	v_div_scale_f32 v16, vcc, 2.0, v9, 2.0
	v_mul_f32_e32 v17, v16, v13
	v_fma_f32 v18, -v12, v17, v16
	v_fmac_f32_e32 v17, v18, v13
	v_fma_f32 v12, -v12, v17, v16
	v_div_fmas_f32 v12, v12, v13, v17
	v_div_fixup_f32 v9, v12, v9, 2.0
	v_div_scale_f32 v12, s[24:25], v8, v8, 2.0
	v_rcp_f32_e32 v13, v12
	s_nop 0
	v_fma_f32 v16, -v12, v13, 1.0
	v_fmac_f32_e32 v13, v16, v13
	v_div_scale_f32 v16, vcc, 2.0, v8, 2.0
	v_mul_f32_e32 v17, v16, v13
	v_fma_f32 v18, -v12, v17, v16
	v_fmac_f32_e32 v17, v18, v13
	v_fma_f32 v12, -v12, v17, v16
	v_div_fmas_f32 v12, v12, v13, v17
	v_div_fixup_f32 v8, v12, v8, 2.0
	v_pk_add_f32 v[8:9], v[8:9], 1.0 op_sel_hi:[1,0] neg_lo:[1,0] neg_hi:[1,0]
	s_nop 0
	v_pk_add_f32 v[8:9], v[8:9], 1.0 op_sel_hi:[1,0]
	s_nop 0
	v_pk_mul_f32 v[12:13], v[6:7], v[8:9]
	v_cvt_pk_bf16_f32 v7, v10, v11
	v_add_co_u32_e32 v10, vcc, 0x8800000, v0
	v_cvt_pk_bf16_f32 v6, v22, v23
	s_nop 0
	v_addc_co_u32_e32 v11, vcc, 0, v1, vcc
	v_cmp_le_u64_e32 vcc, s[20:21], v[4:5]
	v_cvt_pk_bf16_f32 v8, v14, v15
	v_cvt_pk_bf16_f32 v9, v12, v13
	v_lshl_add_u64 v[0:1], v[0:1], 0, s[6:7]
	s_or_b64 s[26:27], vcc, s[26:27]
	global_store_dwordx4 v[10:11], v[6:9], off
	s_andn2_b64 exec, exec, s[26:27]
	s_cbranch_execnz .LBB0_389

; DI void unpack8(u32x4 v, float* f) { f[0] = bflo(v.x); f[1] = bfhi(v.x); f[2] = bflo(v.y); f[3] = bfhi(v.y); f[4] = bflo(v.z); f[5] = bfhi(v.z); f[6] = bflo(v.w); f[7] = bfhi(v.w); }
; DI u32x4 pack8(const float* f) { u32x4 o; o.x = pk2(f[0], f[1]); o.y = pk2(f[2], f[3]); o.z = pk2(f[4], f[5]); o.w = pk2(f[6], f[7]); return o; }
; DI void retcomb_phase(const bf16_t* Z, const bf16_t* OF, const bf16_t* OB, bf16_t* MIX, int gw, int NGW, int lane) {
;     for (int row = gw; row < M; row += NGW) {
;         float f1[8], f2[8], g[8], o[8];
;         unpack8(*(const u32x4*)(OF + (size_t)row * 512 + lane * 8), f1); unpack8(*(const u32x4*)(OB + (size_t)row * 512 + lane * 8), f2);
;         unpack8(*(const u32x4*)(Z + (size_t)row * ZW + 2048 + lane * 8), g);
;         float s = 0.f;
; #pragma unroll
;         for (int q = 0; q < 8; ++q) { o[q] = f1[q] + f2[q]; s += o[q]; }
;         s += __shfl_xor(s, 1); s += __shfl_xor(s, 2); s += __shfl_xor(s, 4);
;         const float mu = s * (1.f / 64.f); float v = 0.f;
; #pragma unroll
;         for (int q = 0; q < 8; ++q) { o[q] -= mu; v += o[q] * o[q]; }
;         v += __shfl_xor(v, 1); v += __shfl_xor(v, 2); v += __shfl_xor(v, 4);
;         const float rs = rsqrtf(v * (1.f / 64.f) + EPS);
; #pragma unroll
;         for (int q = 0; q < 8; ++q) o[q] = o[q] * rs * (g[q] / (1.f + __expf(-g[q])));
;         *(u32x4*)(MIX + (size_t)row * D + 512 + lane * 8) = pack8(o);
;     }
.LBB0_430:
	v_lshl_add_u64 v[14:15], v[8:9], 0, s[78:79]
	v_add_co_u32_e32 v0, vcc, 0x1bedc000, v14
	v_lshl_add_u64 v[18:19], v[6:7], 0, s[78:79]
	s_nop 0
	v_addc_co_u32_e32 v1, vcc, 0, v15, vcc
	v_add_co_u32_e32 v14, vcc, 0x202dc000, v14
	global_load_dwordx4 v[0:3], v[0:1], off
	s_nop 0
	v_addc_co_u32_e32 v15, vcc, 0, v15, vcc
	global_load_dwordx4 v[14:17], v[14:15], off
	s_add_i32 s8, s8, s48
	global_load_dwordx4 v[18:21], v[18:19], off nt
	v_lshl_add_u64 v[6:7], v[6:7], 0, s[4:5]
	v_lshl_add_u64 v[8:9], v[8:9], 0, s[6:7]
	s_cmp_gt_i32 s8, 0x10fff
	s_waitcnt vmcnt(2)
	v_lshlrev_b32_e32 v22, 16, v3
	v_and_b32_e32 v23, 0xffff0000, v3
	s_waitcnt vmcnt(1)
	v_lshlrev_b32_e32 v24, 16, v17
	v_and_b32_e32 v25, 0xffff0000, v17
	s_waitcnt vmcnt(0)
	v_lshlrev_b32_e32 v13, 16, v21
	v_and_b32_e32 v32, 0xffff0000, v21
	v_lshlrev_b32_e32 v21, 16, v20
	v_and_b32_e32 v20, 0xffff0000, v20
	v_pk_add_f32 v[22:23], v[22:23], v[24:25]
	v_lshlrev_b32_e32 v24, 16, v2
	v_and_b32_e32 v25, 0xffff0000, v2
	v_lshlrev_b32_e32 v2, 16, v16
	v_and_b32_e32 v3, 0xffff0000, v16
	v_mul_f32_e32 v16, 0xbfb8aa3b, v21
	v_mul_f32_e32 v17, 0xbfb8aa3b, v20
	v_exp_f32_e32 v16, v16
	v_exp_f32_e32 v17, v17
	v_pk_add_f32 v[2:3], v[24:25], v[2:3]
	v_pk_add_f32 v[16:17], v[16:17], 1.0 op_sel_hi:[1,0]
	s_nop 0
	v_div_scale_f32 v24, s[24:25], v17, v17, v20
	v_rcp_f32_e32 v25, v24
	s_nop 0
	v_fma_f32 v26, -v24, v25, 1.0
	v_fmac_f32_e32 v25, v26, v25
	v_div_scale_f32 v26, vcc, v20, v17, v20
	v_mul_f32_e32 v27, v26, v25
	v_fma_f32 v28, -v24, v27, v26
	v_fmac_f32_e32 v27, v28, v25
	v_fma_f32 v24, -v24, v27, v26
	v_div_fmas_f32 v24, v24, v25, v27
	v_div_fixup_f32 v17, v24, v17, v20
	v_div_scale_f32 v20, s[24:25], v16, v16, v21
	v_rcp_f32_e32 v24, v20
	s_nop 0
	v_fma_f32 v25, -v20, v24, 1.0
	v_fmac_f32_e32 v24, v25, v24
	v_div_scale_f32 v25, vcc, v21, v16, v21
	v_mul_f32_e32 v26, v25, v24
	v_fma_f32 v27, -v20, v26, v25
	v_fmac_f32_e32 v26, v27, v24
	v_fma_f32 v20, -v20, v26, v25
	v_div_fmas_f32 v20, v20, v24, v26
	v_div_fixup_f32 v16, v20, v16, v21
	v_lshlrev_b32_e32 v20, 16, v1
	v_and_b32_e32 v21, 0xffff0000, v1
	v_lshlrev_b32_e32 v1, 16, v19
	v_lshlrev_b32_e32 v24, 16, v15
	v_and_b32_e32 v25, 0xffff0000, v15
	v_and_b32_e32 v15, 0xffff0000, v19
	v_mul_f32_e32 v19, 0xbfb8aa3b, v1
	v_pk_add_f32 v[20:21], v[20:21], v[24:25]
	v_exp_f32_e32 v24, v19
	v_mul_f32_e32 v19, 0xbfb8aa3b, v15
	v_exp_f32_e32 v25, v19
	s_nop 0
	v_pk_add_f32 v[24:25], v[24:25], 1.0 op_sel_hi:[1,0]
	s_nop 0
	v_div_scale_f32 v19, s[24:25], v25, v25, v15
	v_rcp_f32_e32 v26, v19
	s_nop 0
	v_fma_f32 v27, -v19, v26, 1.0
	v_fmac_f32_e32 v26, v27, v26
	v_div_scale_f32 v27, vcc, v15, v25, v15
	v_mul_f32_e32 v28, v27, v26
	v_fma_f32 v29, -v19, v28, v27
	v_fmac_f32_e32 v28, v29, v26
	v_fma_f32 v19, -v19, v28, v27
	v_div_fmas_f32 v19, v19, v26, v28
	v_div_fixup_f32 v25, v19, v25, v15
	v_div_scale_f32 v15, s[24:25], v24, v24, v1
	v_rcp_f32_e32 v19, v15
	s_nop 0
	v_fma_f32 v26, -v15, v19, 1.0
	v_fmac_f32_e32 v19, v26, v19
	v_div_scale_f32 v26, vcc, v1, v24, v1
	v_mul_f32_e32 v27, v26, v19
	v_fma_f32 v28, -v15, v27, v26
	v_fmac_f32_e32 v27, v28, v19
	v_fma_f32 v15, -v15, v27, v26
	v_div_fmas_f32 v15, v15, v19, v27
	v_div_fixup_f32 v24, v15, v24, v1
	v_lshlrev_b32_e32 v26, 16, v0
	v_and_b32_e32 v27, 0xffff0000, v0
	v_lshlrev_b32_e32 v0, 16, v14
	v_and_b32_e32 v1, 0xffff0000, v14
	v_pk_add_f32 v[0:1], v[26:27], v[0:1]
	v_lshlrev_b32_e32 v19, 16, v18
	v_and_b32_e32 v18, 0xffff0000, v18
	v_add_f32_e32 v14, 0, v0
	v_add_f32_e32 v26, v1, v14
	v_mul_f32_e32 v14, 0xbfb8aa3b, v19
	v_mul_f32_e32 v15, 0xbfb8aa3b, v18
	v_exp_f32_e32 v14, v14
	v_exp_f32_e32 v15, v15
	s_nop 0
	v_pk_add_f32 v[14:15], v[14:15], 1.0 op_sel_hi:[1,0]
	s_nop 0
	v_div_scale_f32 v27, s[24:25], v15, v15, v18
	v_rcp_f32_e32 v28, v27
	s_nop 0
	v_fma_f32 v29, -v27, v28, 1.0
	v_fmac_f32_e32 v28, v29, v28
	v_div_scale_f32 v29, vcc, v18, v15, v18
	v_mul_f32_e32 v30, v29, v28
	v_fma_f32 v31, -v27, v30, v29
	v_fmac_f32_e32 v30, v31, v28
	v_fma_f32 v27, -v27, v30, v29
	v_div_fmas_f32 v27, v27, v28, v30
	v_div_fixup_f32 v15, v27, v15, v18
	v_div_scale_f32 v18, s[24:25], v14, v14, v19
	v_rcp_f32_e32 v27, v18
	s_nop 0
	v_fma_f32 v28, -v18, v27, 1.0
	v_fmac_f32_e32 v27, v28, v27
	v_div_scale_f32 v28, vcc, v19, v14, v19
	v_mul_f32_e32 v29, v28, v27
	v_fma_f32 v30, -v18, v29, v28
	v_fmac_f32_e32 v29, v30, v27
	v_fma_f32 v18, -v18, v29, v28
	v_div_fmas_f32 v18, v18, v27, v29
	v_div_fixup_f32 v14, v18, v14, v19
	v_add_f32_e32 v18, v20, v26
	v_add_f32_e32 v18, v21, v18
	v_add_f32_e32 v18, v2, v18
	v_add_f32_e32 v18, v3, v18
	v_add_f32_e32 v18, v22, v18
	v_add_f32_e32 v18, v23, v18
	ds_bpermute_b32 v19, v10, v18
	s_waitcnt lgkmcnt(0)
; DI u32x4 pack8(const float* f) { u32x4 o; o.x = pk2(f[0], f[1]); o.y = pk2(f[2], f[3]); o.z = pk2(f[4], f[5]); o.w = pk2(f[6], f[7]); return o; }
; DI void retcomb_phase(const bf16_t* Z, const bf16_t* OF, const bf16_t* OB, bf16_t* MIX, int gw, int NGW, int lane) {
;     ...
;         s += __shfl_xor(s, 1); s += __shfl_xor(s, 2); s += __shfl_xor(s, 4);
;         const float mu = s * (1.f / 64.f); float v = 0.f;
; #pragma unroll
;         for (int q = 0; q < 8; ++q) { o[q] -= mu; v += o[q] * o[q]; }
;         v += __shfl_xor(v, 1); v += __shfl_xor(v, 2); v += __shfl_xor(v, 4);
;         const float rs = rsqrtf(v * (1.f / 64.f) + EPS);
; #pragma unroll
;         for (int q = 0; q < 8; ++q) o[q] = o[q] * rs * (g[q] / (1.f + __expf(-g[q])));
;         *(u32x4*)(MIX + (size_t)row * D + 512 + lane * 8) = pack8(o);
	v_add_f32_e32 v18, v18, v19
	ds_bpermute_b32 v19, v11, v18
	s_waitcnt lgkmcnt(0)
	v_add_f32_e32 v18, v18, v19
	ds_bpermute_b32 v19, v12, v18
	s_waitcnt lgkmcnt(0)
	v_add_f32_e32 v18, v18, v19
	v_mul_f32_e32 v18, 0x3c800000, v18
	v_pk_add_f32 v[0:1], v[0:1], v[18:19] op_sel_hi:[1,0] neg_lo:[0,1] neg_hi:[0,1]
	v_pk_add_f32 v[20:21], v[20:21], v[18:19] op_sel_hi:[1,0] neg_lo:[0,1] neg_hi:[0,1]
	v_pk_mul_f32 v[26:27], v[0:1], v[0:1]
	v_pk_mul_f32 v[28:29], v[20:21], v[20:21]
	v_add_f32_e32 v26, v26, v27
	v_pk_add_f32 v[2:3], v[2:3], v[18:19] op_sel_hi:[1,0] neg_lo:[0,1] neg_hi:[0,1]
	v_add_f32_e32 v26, v28, v26
	v_pk_mul_f32 v[30:31], v[2:3], v[2:3]
	v_add_f32_e32 v26, v29, v26
	v_pk_add_f32 v[18:19], v[22:23], v[18:19] op_sel_hi:[1,0] neg_lo:[0,1] neg_hi:[0,1]
	v_add_f32_e32 v26, v30, v26
	v_pk_mul_f32 v[22:23], v[18:19], v[18:19]
	v_add_f32_e32 v26, v31, v26
	v_add_f32_e32 v22, v22, v26
	v_add_f32_e32 v22, v23, v22
	ds_bpermute_b32 v23, v10, v22
	s_waitcnt lgkmcnt(0)
	v_add_f32_e32 v22, v22, v23
	ds_bpermute_b32 v23, v11, v22
	s_waitcnt lgkmcnt(0)
	v_add_f32_e32 v22, v22, v23
	ds_bpermute_b32 v23, v12, v22
	s_waitcnt lgkmcnt(0)
	v_add_f32_e32 v22, v22, v23
	v_fmamk_f32 v22, v22, 0x3c800000, v150
	v_cmp_gt_f32_e32 vcc, s62, v22
	v_mul_f32_e32 v23, 0x4b800000, v22
	s_nop 0
	v_cndmask_b32_e32 v22, v22, v23, vcc
	v_rsq_f32_e32 v22, v22
	s_nop 0
	v_mul_f32_e32 v23, 0x45800000, v22
	v_cndmask_b32_e32 v22, v22, v23, vcc
	v_pk_mul_f32 v[2:3], v[2:3], v[22:23] op_sel_hi:[1,0]
	v_pk_mul_f32 v[0:1], v[0:1], v[22:23] op_sel_hi:[1,0]
	v_pk_mul_f32 v[2:3], v[16:17], v[2:3]
	v_mul_f32_e32 v16, 0xbfb8aa3b, v13
	v_mul_f32_e32 v17, 0xbfb8aa3b, v32
	v_exp_f32_e32 v16, v16
	v_exp_f32_e32 v17, v17
	v_pk_mul_f32 v[0:1], v[14:15], v[0:1]
	v_pk_mul_f32 v[14:15], v[20:21], v[22:23] op_sel_hi:[1,0]
	v_pk_mul_f32 v[18:19], v[18:19], v[22:23] op_sel_hi:[1,0]
	v_pk_add_f32 v[16:17], v[16:17], 1.0 op_sel_hi:[1,0]
	v_pk_mul_f32 v[14:15], v[24:25], v[14:15]
	v_div_scale_f32 v20, s[24:25], v17, v17, v32
	v_rcp_f32_e32 v21, v20
	v_cvt_pk_bf16_f32 v0, v0, v1
	v_cvt_pk_bf16_f32 v1, v14, v15
	v_cvt_pk_bf16_f32 v2, v2, v3
	v_fma_f32 v22, -v20, v21, 1.0
	v_fmac_f32_e32 v21, v22, v21
	v_div_scale_f32 v22, vcc, v32, v17, v32
	v_mul_f32_e32 v23, v22, v21
	v_fma_f32 v24, -v20, v23, v22
	v_fmac_f32_e32 v23, v24, v21
	v_fma_f32 v20, -v20, v23, v22
	v_div_fmas_f32 v20, v20, v21, v23
	v_div_fixup_f32 v17, v20, v17, v32
	v_div_scale_f32 v20, s[24:25], v16, v16, v13
	v_rcp_f32_e32 v21, v20
	v_lshl_add_u64 v[14:15], v[4:5], 0, s[78:79]
	v_lshl_add_u64 v[4:5], v[4:5], 0, s[0:1]
	v_fma_f32 v22, -v20, v21, 1.0
	v_fmac_f32_e32 v21, v22, v21
	v_div_scale_f32 v22, vcc, v13, v16, v13
	v_mul_f32_e32 v23, v22, v21
	v_fma_f32 v24, -v20, v23, v22
	v_fmac_f32_e32 v23, v24, v21
	v_fma_f32 v20, -v20, v23, v22
	v_div_fmas_f32 v20, v20, v21, v23
	v_div_fixup_f32 v16, v20, v16, v13
	v_pk_mul_f32 v[16:17], v[16:17], v[18:19]
	s_nop 0
	v_cvt_pk_bf16_f32 v3, v16, v17
	global_store_dwordx4 v[14:15], v[0:3], off
	s_cbranch_scc0 .LBB0_430
